# P4 epilogue rewritten as a streaming pipeline: 24 x loads in flight, per-group counted waits, freed registers reloaded for the last two groups
# baseline (speedup 1.0000x reference)
; __device__ __forceinline__ unsigned cvt_pk_bf16(float lo, float hi) { const f32x2c_t v = {lo, hi}; const bf16x2c_t b = __builtin_convertvector(v, bf16x2c_t); return __builtin_bit_cast(unsigned, b); }
;     __device__ __forceinline__ void operator()(const f32x4 (&acc)[2][2][4][2], const Unit& u, int wr, int wc, int fr, int fq) const {
;         { int l_ = (int)(threadIdx.x & 63u); asm volatile("" : "+v"(l_)); fr = l_ & 15; fq = l_ >> 4; }
;         const int row0 = u.pm * BM + wr * 64 + fr, col0 = u.pn * BM + wc * 32 + 8 * fq;
;         const float* xbase = (u.pm * BM < TP) ? xp : (xs - (size_t)TP * DM);
; #pragma unroll
;         for (int ai = 0; ai < 2; ++ai) {
;             f32x4 xv[4][2][2];
; #pragma unroll
;             for (int m = 0; m < 4; ++m)
; #pragma unroll
;                 for (int bj = 0; bj < 2; ++bj) { const size_t off = (size_t)(row0 + ai * HALF + m * 16) * DM + col0 + bj * HALF; xv[m][bj][0] = *(const f32x4*)(xbase + off); xv[m][bj][1] = *(const f32x4*)(xbase + off + 4); }
; #pragma unroll
;             for (int m = 0; m < 4; ++m) { const size_t r = (size_t)(row0 + ai * HALF + m * 16); float ss = 0.f;
; #pragma unroll
;                 for (int bj = 0; bj < 2; ++bj) { const size_t off = r * DM + col0 + bj * HALF;
;                     const f32x4 v0 = acc[ai][bj][m][0] * ascale + xv[m][bj][0], v1 = acc[ai][bj][m][1] * ascale + xv[m][bj][1];
;                     if (!WB) { *(f32x4*)(out + off) = v0; *(f32x4*)(out + off + 4) = v1; }
;                     if (WB) { u32x4 w; w.x = cvt_pk_bf16(v0[0], v0[1]); w.y = cvt_pk_bf16(v0[2], v0[3]); w.z = cvt_pk_bf16(v1[0], v1[1]); w.w = cvt_pk_bf16(v1[2], v1[3]); *(u32x4*)(xb + off) = w; }
;                     ss += (v0[0] * v0[0] + v0[1] * v0[1]) + (v0[2] * v0[2] + v0[3] * v0[3]) + (v1[0] * v1[0] + v1[1] * v1[1]) + (v1[2] * v1[2] + v1[3] * v1[3]); }
;                 ss += __shfl_xor(ss, 16); ss += __shfl_xor(ss, 32);
;                 if (fq == 0) ssq[r * 16 + u.pn * 4 + wc] = ss; }
;             asm volatile("" ::: "memory"); }
;     }
.LBB0_345:
	s_lshl_b32 s0, s52, 8
	v_and_b32_e32 v178, 63, v254
	s_add_i32 s0, s0, s64
	v_and_or_b32 v196, v178, 15, s0
	s_lshl_b32 s0, s50, 8
	s_or_b32 s0, s0, s65
	v_ashrrev_i32_e32 v207, 1, v178
	v_and_b32_e32 v207, -8, v207
	v_add_u32_e32 v207, s0, v207
	s_cmp_lt_i32 s52, 64
	s_cselect_b32 s0, s37, s62
	s_cselect_b32 s1, s36, s61
	v_mov_b32_e32 v252, s1
	v_mov_b32_e32 v253, s0
	v_mov_b32_e32 v224, v196
	v_ashrrev_i32_e32 v225, 31, v196
	v_mov_b32_e32 v226, v207
	v_ashrrev_i32_e32 v227, 31, v207
	v_lshl_add_u64 v[252:253], v[226:227], 2, v[252:253]
	v_lshlrev_b64 v[250:251], 12, v[224:225]
	v_lshl_add_u64 v[252:253], v[252:253], 0, v[250:251]
	s_lshl_b32 s0, s50, 4
	s_lshl_b32 s1, s63, 2
	s_add_u32 s0, s0, s1
	s_mov_b32 s1, 0
	v_lshlrev_b64 v[248:249], 6, v[224:225]
	v_lshl_add_u64 v[248:249], s[12:13], 0, v[248:249]
	v_lshl_add_u64 v[248:249], v[248:249], 0, s[0:1]
	v_lshlrev_b64 v[250:251], 11, v[224:225]
	v_lshl_add_u64 v[250:251], s[16:17], 0, v[250:251]
	v_lshl_add_u64 v[224:225], v[226:227], 1, v[250:251]
	v_mov_b64_e32 v[226:227], v[248:249]
	s_mov_b64 s[78:79], 0x10000
	s_mov_b64 s[80:81], 0x50000
	s_mov_b64 s[82:83], 0x8000
	s_mov_b64 s[84:85], 0x28000
	s_mov_b64 s[86:87], 0x400
	s_mov_b64 s[88:89], 0x1400
	global_load_dwordx4 v[128:131], v[252:253], off
	global_load_dwordx4 v[132:135], v[252:253], off offset:16
	global_load_dwordx4 v[136:139], v[252:253], off offset:512
	global_load_dwordx4 v[140:143], v[252:253], off offset:528
	v_lshl_add_u64 v[252:253], v[252:253], 0, s[78:79]
	global_load_dwordx4 v[144:147], v[252:253], off
	global_load_dwordx4 v[148:151], v[252:253], off offset:16
	global_load_dwordx4 v[152:155], v[252:253], off offset:512
	global_load_dwordx4 v[156:159], v[252:253], off offset:528
	v_lshl_add_u64 v[252:253], v[252:253], 0, s[78:79]
	global_load_dwordx4 v[160:163], v[252:253], off
	global_load_dwordx4 v[164:167], v[252:253], off offset:16
	global_load_dwordx4 v[168:171], v[252:253], off offset:512
	global_load_dwordx4 v[172:175], v[252:253], off offset:528
	v_lshl_add_u64 v[252:253], v[252:253], 0, s[78:79]
	global_load_dwordx4 v[180:183], v[252:253], off
	global_load_dwordx4 v[184:187], v[252:253], off offset:16
	global_load_dwordx4 v[188:191], v[252:253], off offset:512
	global_load_dwordx4 v[192:195], v[252:253], off offset:528
	v_lshl_add_u64 v[252:253], v[252:253], 0, s[80:81]
	global_load_dwordx4 v[208:211], v[252:253], off
	global_load_dwordx4 v[212:215], v[252:253], off offset:16
	global_load_dwordx4 v[216:219], v[252:253], off offset:512
	global_load_dwordx4 v[220:223], v[252:253], off offset:528
	v_lshl_add_u64 v[252:253], v[252:253], 0, s[78:79]
	global_load_dwordx4 v[236:239], v[252:253], off
	global_load_dwordx4 v[240:243], v[252:253], off offset:16
	global_load_dwordx4 v[244:247], v[252:253], off offset:512
	global_load_dwordx4 v[248:251], v[252:253], off offset:528
	v_lshl_add_u64 v[252:253], v[252:253], 0, s[78:79]
	v_and_b32_e32 v196, 64, v204
	v_add_u32_e32 v196, 64, v196
	v_xor_b32_e32 v205, 16, v204
	v_cmp_lt_i32_e32 vcc, v205, v196
	s_nop 1
	v_cndmask_b32_e32 v205, v204, v205, vcc
	v_lshlrev_b32_e32 v205, 2, v205
	v_xor_b32_e32 v206, 32, v204
	v_cmp_lt_i32_e32 vcc, v206, v196
	s_nop 1
	v_cndmask_b32_e32 v206, v204, v206, vcc
	v_lshlrev_b32_e32 v206, 2, v206
	v_cmp_gt_u32_e32 vcc, 16, v178
	s_waitcnt vmcnt(20)
	v_pk_fma_f32 v[116:117], v[116:117], s[40:41], v[128:129] op_sel_hi:[1,0,1]
	v_pk_fma_f32 v[118:119], v[118:119], s[40:41], v[130:131] op_sel_hi:[1,0,1]
	v_pk_fma_f32 v[112:113], v[112:113], s[40:41], v[132:133] op_sel_hi:[1,0,1]
	v_pk_fma_f32 v[114:115], v[114:115], s[40:41], v[134:135] op_sel_hi:[1,0,1]
	v_pk_fma_f32 v[124:125], v[124:125], s[40:41], v[136:137] op_sel_hi:[1,0,1]
	v_pk_fma_f32 v[126:127], v[126:127], s[40:41], v[138:139] op_sel_hi:[1,0,1]
	v_pk_fma_f32 v[120:121], v[120:121], s[40:41], v[140:141] op_sel_hi:[1,0,1]
	v_pk_fma_f32 v[122:123], v[122:123], s[40:41], v[142:143] op_sel_hi:[1,0,1]
	v_mul_f32_e32 v128, v117, v117
	v_mul_f32_e32 v129, v119, v119
	v_mul_f32_e32 v130, v113, v113
	v_mul_f32_e32 v131, v115, v115
	v_mul_f32_e32 v132, v125, v125
	v_mul_f32_e32 v133, v127, v127
	v_mul_f32_e32 v134, v121, v121
	v_mul_f32_e32 v135, v123, v123
	v_fmac_f32_e32 v128, v116, v116
	v_fmac_f32_e32 v129, v118, v118
	v_fmac_f32_e32 v130, v112, v112
	v_fmac_f32_e32 v131, v114, v114
	v_fmac_f32_e32 v132, v124, v124
	v_fmac_f32_e32 v133, v126, v126
	v_fmac_f32_e32 v134, v120, v120
	v_fmac_f32_e32 v135, v122, v122
	v_cvt_pk_bf16_f32 v136, v116, v117
	v_cvt_pk_bf16_f32 v137, v118, v119
	v_cvt_pk_bf16_f32 v138, v112, v113
	v_cvt_pk_bf16_f32 v139, v114, v115
	v_cvt_pk_bf16_f32 v140, v124, v125
	v_cvt_pk_bf16_f32 v141, v126, v127
	v_cvt_pk_bf16_f32 v142, v120, v121
	v_cvt_pk_bf16_f32 v143, v122, v123
	global_store_dwordx4 v[224:225], v[136:139], off
	global_store_dwordx4 v[224:225], v[140:143], off offset:256
	v_add_f32_e32 v128, v128, v129
	v_add_f32_e32 v130, v130, v131
	v_add_f32_e32 v132, v132, v133
	v_add_f32_e32 v134, v134, v135
	v_add_f32_e32 v128, v128, v130
	v_add_f32_e32 v132, v132, v134
	v_add_f32_e32 v128, v128, v132
	ds_bpermute_b32 v129, v205, v128
	s_waitcnt lgkmcnt(0)
	v_add_f32_e32 v128, v128, v129
	ds_bpermute_b32 v129, v206, v128
	s_waitcnt lgkmcnt(0)
	v_add_f32_e32 v128, v128, v129
	s_and_saveexec_b64 s[50:51], vcc
	global_store_dword v[226:227], v128, off
	s_or_b64 exec, exec, s[50:51]
	v_lshl_add_u64 v[224:225], v[224:225], 0, s[82:83]
	v_lshl_add_u64 v[226:227], v[226:227], 0, s[86:87]
	global_load_dwordx4 v[128:131], v[252:253], off
	global_load_dwordx4 v[132:135], v[252:253], off offset:16
	global_load_dwordx4 v[136:139], v[252:253], off offset:512
	global_load_dwordx4 v[140:143], v[252:253], off offset:528
	v_lshl_add_u64 v[252:253], v[252:253], 0, s[78:79]
	s_waitcnt vmcnt(23)
; __device__ __forceinline__ unsigned cvt_pk_bf16(float lo, float hi) { const f32x2c_t v = {lo, hi}; const bf16x2c_t b = __builtin_convertvector(v, bf16x2c_t); return __builtin_bit_cast(unsigned, b); }
;     __device__ __forceinline__ void operator()(const f32x4 (&acc)[2][2][4][2], const Unit& u, int wr, int wc, int fr, int fq) const {
;     ...
;                 for (int bj = 0; bj < 2; ++bj) { const size_t off = (size_t)(row0 + ai * HALF + m * 16) * DM + col0 + bj * HALF; xv[m][bj][0] = *(const f32x4*)(xbase + off); xv[m][bj][1] = *(const f32x4*)(xbase + off + 4); }
; #pragma unroll
;             for (int m = 0; m < 4; ++m) { const size_t r = (size_t)(row0 + ai * HALF + m * 16); float ss = 0.f;
; #pragma unroll
;                 for (int bj = 0; bj < 2; ++bj) { const size_t off = r * DM + col0 + bj * HALF;
;                     const f32x4 v0 = acc[ai][bj][m][0] * ascale + xv[m][bj][0], v1 = acc[ai][bj][m][1] * ascale + xv[m][bj][1];
;                     if (!WB) { *(f32x4*)(out + off) = v0; *(f32x4*)(out + off + 4) = v1; }
;                     if (WB) { u32x4 w; w.x = cvt_pk_bf16(v0[0], v0[1]); w.y = cvt_pk_bf16(v0[2], v0[3]); w.z = cvt_pk_bf16(v1[0], v1[1]); w.w = cvt_pk_bf16(v1[2], v1[3]); *(u32x4*)(xb + off) = w; }
;                     ss += (v0[0] * v0[0] + v0[1] * v0[1]) + (v0[2] * v0[2] + v0[3] * v0[3]) + (v1[0] * v1[0] + v1[1] * v1[1]) + (v1[2] * v1[2] + v1[3] * v1[3]); }
;                 ss += __shfl_xor(ss, 16); ss += __shfl_xor(ss, 32);
;                 if (fq == 0) ssq[r * 16 + u.pn * 4 + wc] = ss; }
	v_pk_fma_f32 v[108:109], v[108:109], s[40:41], v[144:145] op_sel_hi:[1,0,1]
	v_pk_fma_f32 v[110:111], v[110:111], s[40:41], v[146:147] op_sel_hi:[1,0,1]
	v_pk_fma_f32 v[100:101], v[100:101], s[40:41], v[148:149] op_sel_hi:[1,0,1]
	v_pk_fma_f32 v[102:103], v[102:103], s[40:41], v[150:151] op_sel_hi:[1,0,1]
	v_pk_fma_f32 v[104:105], v[104:105], s[40:41], v[152:153] op_sel_hi:[1,0,1]
	v_pk_fma_f32 v[106:107], v[106:107], s[40:41], v[154:155] op_sel_hi:[1,0,1]
	v_pk_fma_f32 v[96:97], v[96:97], s[40:41], v[156:157] op_sel_hi:[1,0,1]
	v_pk_fma_f32 v[98:99], v[98:99], s[40:41], v[158:159] op_sel_hi:[1,0,1]
	v_mul_f32_e32 v144, v109, v109
	v_mul_f32_e32 v145, v111, v111
	v_mul_f32_e32 v146, v101, v101
	v_mul_f32_e32 v147, v103, v103
	v_mul_f32_e32 v148, v105, v105
	v_mul_f32_e32 v149, v107, v107
	v_mul_f32_e32 v150, v97, v97
	v_mul_f32_e32 v151, v99, v99
	v_fmac_f32_e32 v144, v108, v108
	v_fmac_f32_e32 v145, v110, v110
	v_fmac_f32_e32 v146, v100, v100
	v_fmac_f32_e32 v147, v102, v102
	v_fmac_f32_e32 v148, v104, v104
	v_fmac_f32_e32 v149, v106, v106
	v_fmac_f32_e32 v150, v96, v96
	v_fmac_f32_e32 v151, v98, v98
	v_cvt_pk_bf16_f32 v152, v108, v109
	v_cvt_pk_bf16_f32 v153, v110, v111
	v_cvt_pk_bf16_f32 v154, v100, v101
	v_cvt_pk_bf16_f32 v155, v102, v103
	v_cvt_pk_bf16_f32 v156, v104, v105
	v_cvt_pk_bf16_f32 v157, v106, v107
	v_cvt_pk_bf16_f32 v158, v96, v97
	v_cvt_pk_bf16_f32 v159, v98, v99
	global_store_dwordx4 v[224:225], v[152:155], off
	global_store_dwordx4 v[224:225], v[156:159], off offset:256
	v_add_f32_e32 v144, v144, v145
	v_add_f32_e32 v146, v146, v147
	v_add_f32_e32 v148, v148, v149
	v_add_f32_e32 v150, v150, v151
	v_add_f32_e32 v144, v144, v146
	v_add_f32_e32 v148, v148, v150
	v_add_f32_e32 v144, v144, v148
	ds_bpermute_b32 v145, v205, v144
	s_waitcnt lgkmcnt(0)
	v_add_f32_e32 v144, v144, v145
	ds_bpermute_b32 v145, v206, v144
	s_waitcnt lgkmcnt(0)
	v_add_f32_e32 v144, v144, v145
	s_and_saveexec_b64 s[50:51], vcc
	global_store_dword v[226:227], v144, off
	s_or_b64 exec, exec, s[50:51]
	v_lshl_add_u64 v[224:225], v[224:225], 0, s[82:83]
	v_lshl_add_u64 v[226:227], v[226:227], 0, s[86:87]
	global_load_dwordx4 v[144:147], v[252:253], off
	global_load_dwordx4 v[148:151], v[252:253], off offset:16
	global_load_dwordx4 v[152:155], v[252:253], off offset:512
	global_load_dwordx4 v[156:159], v[252:253], off offset:528
	s_waitcnt vmcnt(26)
	v_pk_fma_f32 v[92:93], v[92:93], s[40:41], v[160:161] op_sel_hi:[1,0,1]
	v_pk_fma_f32 v[94:95], v[94:95], s[40:41], v[162:163] op_sel_hi:[1,0,1]
	v_pk_fma_f32 v[84:85], v[84:85], s[40:41], v[164:165] op_sel_hi:[1,0,1]
	v_pk_fma_f32 v[86:87], v[86:87], s[40:41], v[166:167] op_sel_hi:[1,0,1]
	v_pk_fma_f32 v[88:89], v[88:89], s[40:41], v[168:169] op_sel_hi:[1,0,1]
	v_pk_fma_f32 v[90:91], v[90:91], s[40:41], v[170:171] op_sel_hi:[1,0,1]
	v_pk_fma_f32 v[80:81], v[80:81], s[40:41], v[172:173] op_sel_hi:[1,0,1]
	v_pk_fma_f32 v[82:83], v[82:83], s[40:41], v[174:175] op_sel_hi:[1,0,1]
	v_mul_f32_e32 v160, v93, v93
	v_mul_f32_e32 v161, v95, v95
	v_mul_f32_e32 v162, v85, v85
	v_mul_f32_e32 v163, v87, v87
	v_mul_f32_e32 v164, v89, v89
	v_mul_f32_e32 v165, v91, v91
	v_mul_f32_e32 v166, v81, v81
	v_mul_f32_e32 v167, v83, v83
	v_fmac_f32_e32 v160, v92, v92
	v_fmac_f32_e32 v161, v94, v94
	v_fmac_f32_e32 v162, v84, v84
	v_fmac_f32_e32 v163, v86, v86
	v_fmac_f32_e32 v164, v88, v88
	v_fmac_f32_e32 v165, v90, v90
	v_fmac_f32_e32 v166, v80, v80
	v_fmac_f32_e32 v167, v82, v82
	v_cvt_pk_bf16_f32 v168, v92, v93
	v_cvt_pk_bf16_f32 v169, v94, v95
	v_cvt_pk_bf16_f32 v170, v84, v85
	v_cvt_pk_bf16_f32 v171, v86, v87
	v_cvt_pk_bf16_f32 v172, v88, v89
	v_cvt_pk_bf16_f32 v173, v90, v91
	v_cvt_pk_bf16_f32 v174, v80, v81
	v_cvt_pk_bf16_f32 v175, v82, v83
	global_store_dwordx4 v[224:225], v[168:171], off
	global_store_dwordx4 v[224:225], v[172:175], off offset:256
	v_add_f32_e32 v160, v160, v161
	v_add_f32_e32 v162, v162, v163
	v_add_f32_e32 v164, v164, v165
	v_add_f32_e32 v166, v166, v167
	v_add_f32_e32 v160, v160, v162
	v_add_f32_e32 v164, v164, v166
	v_add_f32_e32 v160, v160, v164
	ds_bpermute_b32 v161, v205, v160
	s_waitcnt lgkmcnt(0)
	v_add_f32_e32 v160, v160, v161
	ds_bpermute_b32 v161, v206, v160
	s_waitcnt lgkmcnt(0)
	v_add_f32_e32 v160, v160, v161
	s_and_saveexec_b64 s[50:51], vcc
	global_store_dword v[226:227], v160, off
	s_or_b64 exec, exec, s[50:51]
	v_lshl_add_u64 v[224:225], v[224:225], 0, s[82:83]
	v_lshl_add_u64 v[226:227], v[226:227], 0, s[86:87]
	s_waitcnt vmcnt(25)
	v_pk_fma_f32 v[76:77], v[76:77], s[40:41], v[180:181] op_sel_hi:[1,0,1]
	v_pk_fma_f32 v[78:79], v[78:79], s[40:41], v[182:183] op_sel_hi:[1,0,1]
	v_pk_fma_f32 v[68:69], v[68:69], s[40:41], v[184:185] op_sel_hi:[1,0,1]
	v_pk_fma_f32 v[70:71], v[70:71], s[40:41], v[186:187] op_sel_hi:[1,0,1]
	v_pk_fma_f32 v[72:73], v[72:73], s[40:41], v[188:189] op_sel_hi:[1,0,1]
	v_pk_fma_f32 v[74:75], v[74:75], s[40:41], v[190:191] op_sel_hi:[1,0,1]
	v_pk_fma_f32 v[64:65], v[64:65], s[40:41], v[192:193] op_sel_hi:[1,0,1]
	v_pk_fma_f32 v[66:67], v[66:67], s[40:41], v[194:195] op_sel_hi:[1,0,1]
	v_mul_f32_e32 v180, v77, v77
	v_mul_f32_e32 v181, v79, v79
	v_mul_f32_e32 v182, v69, v69
	v_mul_f32_e32 v183, v71, v71
	v_mul_f32_e32 v184, v73, v73
	v_mul_f32_e32 v185, v75, v75
	v_mul_f32_e32 v186, v65, v65
	v_mul_f32_e32 v187, v67, v67
	v_fmac_f32_e32 v180, v76, v76
	v_fmac_f32_e32 v181, v78, v78
	v_fmac_f32_e32 v182, v68, v68
	v_fmac_f32_e32 v183, v70, v70
	v_fmac_f32_e32 v184, v72, v72
	v_fmac_f32_e32 v185, v74, v74
	v_fmac_f32_e32 v186, v64, v64
	v_fmac_f32_e32 v187, v66, v66
	v_cvt_pk_bf16_f32 v188, v76, v77
	v_cvt_pk_bf16_f32 v189, v78, v79
	v_cvt_pk_bf16_f32 v190, v68, v69
	v_cvt_pk_bf16_f32 v191, v70, v71
	v_cvt_pk_bf16_f32 v192, v72, v73
	v_cvt_pk_bf16_f32 v193, v74, v75
	v_cvt_pk_bf16_f32 v194, v64, v65
	v_cvt_pk_bf16_f32 v195, v66, v67
	global_store_dwordx4 v[224:225], v[188:191], off
	global_store_dwordx4 v[224:225], v[192:195], off offset:256
	v_add_f32_e32 v180, v180, v181
	v_add_f32_e32 v182, v182, v183
	v_add_f32_e32 v184, v184, v185
	v_add_f32_e32 v186, v186, v187
	v_add_f32_e32 v180, v180, v182
	v_add_f32_e32 v184, v184, v186
	v_add_f32_e32 v180, v180, v184
	ds_bpermute_b32 v181, v205, v180
	s_waitcnt lgkmcnt(0)
; __device__ __forceinline__ unsigned cvt_pk_bf16(float lo, float hi) { const f32x2c_t v = {lo, hi}; const bf16x2c_t b = __builtin_convertvector(v, bf16x2c_t); return __builtin_bit_cast(unsigned, b); }
;     __device__ __forceinline__ void operator()(const f32x4 (&acc)[2][2][4][2], const Unit& u, int wr, int wc, int fr, int fq) const {
;     ...
;                 for (int bj = 0; bj < 2; ++bj) { const size_t off = (size_t)(row0 + ai * HALF + m * 16) * DM + col0 + bj * HALF; xv[m][bj][0] = *(const f32x4*)(xbase + off); xv[m][bj][1] = *(const f32x4*)(xbase + off + 4); }
; #pragma unroll
;             for (int m = 0; m < 4; ++m) { const size_t r = (size_t)(row0 + ai * HALF + m * 16); float ss = 0.f;
; #pragma unroll
;                 for (int bj = 0; bj < 2; ++bj) { const size_t off = r * DM + col0 + bj * HALF;
;                     const f32x4 v0 = acc[ai][bj][m][0] * ascale + xv[m][bj][0], v1 = acc[ai][bj][m][1] * ascale + xv[m][bj][1];
;                     if (!WB) { *(f32x4*)(out + off) = v0; *(f32x4*)(out + off + 4) = v1; }
;                     if (WB) { u32x4 w; w.x = cvt_pk_bf16(v0[0], v0[1]); w.y = cvt_pk_bf16(v0[2], v0[3]); w.z = cvt_pk_bf16(v1[0], v1[1]); w.w = cvt_pk_bf16(v1[2], v1[3]); *(u32x4*)(xb + off) = w; }
;                     ss += (v0[0] * v0[0] + v0[1] * v0[1]) + (v0[2] * v0[2] + v0[3] * v0[3]) + (v1[0] * v1[0] + v1[1] * v1[1]) + (v1[2] * v1[2] + v1[3] * v1[3]); }
;                 ss += __shfl_xor(ss, 16); ss += __shfl_xor(ss, 32);
;                 if (fq == 0) ssq[r * 16 + u.pn * 4 + wc] = ss; }
	v_add_f32_e32 v180, v180, v181
	ds_bpermute_b32 v181, v206, v180
	s_waitcnt lgkmcnt(0)
	v_add_f32_e32 v180, v180, v181
	s_and_saveexec_b64 s[50:51], vcc
	global_store_dword v[226:227], v180, off
	s_or_b64 exec, exec, s[50:51]
	v_lshl_add_u64 v[224:225], v[224:225], 0, s[84:85]
	v_lshl_add_u64 v[226:227], v[226:227], 0, s[88:89]
	s_waitcnt vmcnt(24)
	v_pk_fma_f32 v[52:53], v[52:53], s[40:41], v[208:209] op_sel_hi:[1,0,1]
	v_pk_fma_f32 v[54:55], v[54:55], s[40:41], v[210:211] op_sel_hi:[1,0,1]
	v_pk_fma_f32 v[48:49], v[48:49], s[40:41], v[212:213] op_sel_hi:[1,0,1]
	v_pk_fma_f32 v[50:51], v[50:51], s[40:41], v[214:215] op_sel_hi:[1,0,1]
	v_pk_fma_f32 v[60:61], v[60:61], s[40:41], v[216:217] op_sel_hi:[1,0,1]
	v_pk_fma_f32 v[62:63], v[62:63], s[40:41], v[218:219] op_sel_hi:[1,0,1]
	v_pk_fma_f32 v[56:57], v[56:57], s[40:41], v[220:221] op_sel_hi:[1,0,1]
	v_pk_fma_f32 v[58:59], v[58:59], s[40:41], v[222:223] op_sel_hi:[1,0,1]
	v_mul_f32_e32 v208, v53, v53
	v_mul_f32_e32 v209, v55, v55
	v_mul_f32_e32 v210, v49, v49
	v_mul_f32_e32 v211, v51, v51
	v_mul_f32_e32 v212, v61, v61
	v_mul_f32_e32 v213, v63, v63
	v_mul_f32_e32 v214, v57, v57
	v_mul_f32_e32 v215, v59, v59
	v_fmac_f32_e32 v208, v52, v52
	v_fmac_f32_e32 v209, v54, v54
	v_fmac_f32_e32 v210, v48, v48
	v_fmac_f32_e32 v211, v50, v50
	v_fmac_f32_e32 v212, v60, v60
	v_fmac_f32_e32 v213, v62, v62
	v_fmac_f32_e32 v214, v56, v56
	v_fmac_f32_e32 v215, v58, v58
	v_cvt_pk_bf16_f32 v216, v52, v53
	v_cvt_pk_bf16_f32 v217, v54, v55
	v_cvt_pk_bf16_f32 v218, v48, v49
	v_cvt_pk_bf16_f32 v219, v50, v51
	v_cvt_pk_bf16_f32 v220, v60, v61
	v_cvt_pk_bf16_f32 v221, v62, v63
	v_cvt_pk_bf16_f32 v222, v56, v57
	v_cvt_pk_bf16_f32 v223, v58, v59
	global_store_dwordx4 v[224:225], v[216:219], off
	global_store_dwordx4 v[224:225], v[220:223], off offset:256
	v_add_f32_e32 v208, v208, v209
	v_add_f32_e32 v210, v210, v211
	v_add_f32_e32 v212, v212, v213
	v_add_f32_e32 v214, v214, v215
	v_add_f32_e32 v208, v208, v210
	v_add_f32_e32 v212, v212, v214
	v_add_f32_e32 v208, v208, v212
	ds_bpermute_b32 v209, v205, v208
	s_waitcnt lgkmcnt(0)
	v_add_f32_e32 v208, v208, v209
	ds_bpermute_b32 v209, v206, v208
	s_waitcnt lgkmcnt(0)
	v_add_f32_e32 v208, v208, v209
	s_and_saveexec_b64 s[50:51], vcc
	global_store_dword v[226:227], v208, off
	s_or_b64 exec, exec, s[50:51]
	v_lshl_add_u64 v[224:225], v[224:225], 0, s[82:83]
	v_lshl_add_u64 v[226:227], v[226:227], 0, s[86:87]
	s_waitcnt vmcnt(23)
	v_pk_fma_f32 v[44:45], v[44:45], s[40:41], v[236:237] op_sel_hi:[1,0,1]
	v_pk_fma_f32 v[46:47], v[46:47], s[40:41], v[238:239] op_sel_hi:[1,0,1]
	v_pk_fma_f32 v[36:37], v[36:37], s[40:41], v[240:241] op_sel_hi:[1,0,1]
	v_pk_fma_f32 v[38:39], v[38:39], s[40:41], v[242:243] op_sel_hi:[1,0,1]
	v_pk_fma_f32 v[40:41], v[40:41], s[40:41], v[244:245] op_sel_hi:[1,0,1]
	v_pk_fma_f32 v[42:43], v[42:43], s[40:41], v[246:247] op_sel_hi:[1,0,1]
	v_pk_fma_f32 v[32:33], v[32:33], s[40:41], v[248:249] op_sel_hi:[1,0,1]
	v_pk_fma_f32 v[34:35], v[34:35], s[40:41], v[250:251] op_sel_hi:[1,0,1]
	v_mul_f32_e32 v236, v45, v45
	v_mul_f32_e32 v237, v47, v47
	v_mul_f32_e32 v238, v37, v37
	v_mul_f32_e32 v239, v39, v39
	v_mul_f32_e32 v240, v41, v41
	v_mul_f32_e32 v241, v43, v43
	v_mul_f32_e32 v242, v33, v33
	v_mul_f32_e32 v243, v35, v35
	v_fmac_f32_e32 v236, v44, v44
	v_fmac_f32_e32 v237, v46, v46
	v_fmac_f32_e32 v238, v36, v36
	v_fmac_f32_e32 v239, v38, v38
	v_fmac_f32_e32 v240, v40, v40
	v_fmac_f32_e32 v241, v42, v42
	v_fmac_f32_e32 v242, v32, v32
	v_fmac_f32_e32 v243, v34, v34
	v_cvt_pk_bf16_f32 v244, v44, v45
	v_cvt_pk_bf16_f32 v245, v46, v47
	v_cvt_pk_bf16_f32 v246, v36, v37
	v_cvt_pk_bf16_f32 v247, v38, v39
	v_cvt_pk_bf16_f32 v248, v40, v41
	v_cvt_pk_bf16_f32 v249, v42, v43
	v_cvt_pk_bf16_f32 v250, v32, v33
	v_cvt_pk_bf16_f32 v251, v34, v35
	global_store_dwordx4 v[224:225], v[244:247], off
	global_store_dwordx4 v[224:225], v[248:251], off offset:256
	v_add_f32_e32 v236, v236, v237
	v_add_f32_e32 v238, v238, v239
	v_add_f32_e32 v240, v240, v241
	v_add_f32_e32 v242, v242, v243
	v_add_f32_e32 v236, v236, v238
	v_add_f32_e32 v240, v240, v242
	v_add_f32_e32 v236, v236, v240
	ds_bpermute_b32 v237, v205, v236
	s_waitcnt lgkmcnt(0)
	v_add_f32_e32 v236, v236, v237
	ds_bpermute_b32 v237, v206, v236
	s_waitcnt lgkmcnt(0)
	v_add_f32_e32 v236, v236, v237
	s_and_saveexec_b64 s[50:51], vcc
	global_store_dword v[226:227], v236, off
	s_or_b64 exec, exec, s[50:51]
	v_lshl_add_u64 v[224:225], v[224:225], 0, s[82:83]
	v_lshl_add_u64 v[226:227], v[226:227], 0, s[86:87]
	s_waitcnt vmcnt(19)
	v_pk_fma_f32 v[28:29], v[28:29], s[40:41], v[128:129] op_sel_hi:[1,0,1]
	v_pk_fma_f32 v[30:31], v[30:31], s[40:41], v[130:131] op_sel_hi:[1,0,1]
	v_pk_fma_f32 v[20:21], v[20:21], s[40:41], v[132:133] op_sel_hi:[1,0,1]
	v_pk_fma_f32 v[22:23], v[22:23], s[40:41], v[134:135] op_sel_hi:[1,0,1]
	v_pk_fma_f32 v[24:25], v[24:25], s[40:41], v[136:137] op_sel_hi:[1,0,1]
	v_pk_fma_f32 v[26:27], v[26:27], s[40:41], v[138:139] op_sel_hi:[1,0,1]
	v_pk_fma_f32 v[16:17], v[16:17], s[40:41], v[140:141] op_sel_hi:[1,0,1]
	v_pk_fma_f32 v[18:19], v[18:19], s[40:41], v[142:143] op_sel_hi:[1,0,1]
	v_mul_f32_e32 v128, v29, v29
	v_mul_f32_e32 v129, v31, v31
	v_mul_f32_e32 v130, v21, v21
	v_mul_f32_e32 v131, v23, v23
	v_mul_f32_e32 v132, v25, v25
	v_mul_f32_e32 v133, v27, v27
	v_mul_f32_e32 v134, v17, v17
	v_mul_f32_e32 v135, v19, v19
	v_fmac_f32_e32 v128, v28, v28
	v_fmac_f32_e32 v129, v30, v30
	v_fmac_f32_e32 v130, v20, v20
	v_fmac_f32_e32 v131, v22, v22
	v_fmac_f32_e32 v132, v24, v24
	v_fmac_f32_e32 v133, v26, v26
	v_fmac_f32_e32 v134, v16, v16
	v_fmac_f32_e32 v135, v18, v18
	v_cvt_pk_bf16_f32 v136, v28, v29
	v_cvt_pk_bf16_f32 v137, v30, v31
	v_cvt_pk_bf16_f32 v138, v20, v21
	v_cvt_pk_bf16_f32 v139, v22, v23
	v_cvt_pk_bf16_f32 v140, v24, v25
	v_cvt_pk_bf16_f32 v141, v26, v27
	v_cvt_pk_bf16_f32 v142, v16, v17
	v_cvt_pk_bf16_f32 v143, v18, v19
	global_store_dwordx4 v[224:225], v[136:139], off
	global_store_dwordx4 v[224:225], v[140:143], off offset:256
	v_add_f32_e32 v128, v128, v129
	v_add_f32_e32 v130, v130, v131
	v_add_f32_e32 v132, v132, v133
	v_add_f32_e32 v134, v134, v135
	v_add_f32_e32 v128, v128, v130
	v_add_f32_e32 v132, v132, v134
	v_add_f32_e32 v128, v128, v132
	ds_bpermute_b32 v129, v205, v128
	s_waitcnt lgkmcnt(0)
; __device__ __forceinline__ unsigned cvt_pk_bf16(float lo, float hi) { const f32x2c_t v = {lo, hi}; const bf16x2c_t b = __builtin_convertvector(v, bf16x2c_t); return __builtin_bit_cast(unsigned, b); }
; template <class Epi, class Sched, bool ALIGN_EPI = false, bool SP2 = false, bool FP8 = false>
; __device__ __forceinline__ void gemm_phase(PG8_LAS unsigned char* lds, const Gemm g, const Sched& S, const Epi& E) {
;     ...
; #pragma unroll
;         for (int a = 0; a < 2; ++a)
; #pragma unroll
;             for (int b = 0; b < 2; ++b)
; #pragma unroll
;                 for (int m = 0; m < 4; ++m)
; #pragma unroll
;                     for (int n = 0; n < 2; ++n) { acc[a][b][m][n] = (f32x4){0.f, 0.f, 0.f, 0.f}; if constexpr (FP8) asm volatile("" : "+v"(acc[a][b][m][n])); }
;         cur = nxt; cA = nA; cB = nB; ++ui;
;     __device__ __forceinline__ void operator()(const f32x4 (&acc)[2][2][4][2], const Unit& u, int wr, int wc, int fr, int fq) const {
;     ...
;             for (int m = 0; m < 4; ++m) { const size_t r = (size_t)(row0 + ai * HALF + m * 16); float ss = 0.f;
; #pragma unroll
;                 for (int bj = 0; bj < 2; ++bj) { const size_t off = r * DM + col0 + bj * HALF;
;                     const f32x4 v0 = acc[ai][bj][m][0] * ascale + xv[m][bj][0], v1 = acc[ai][bj][m][1] * ascale + xv[m][bj][1];
;                     if (!WB) { *(f32x4*)(out + off) = v0; *(f32x4*)(out + off + 4) = v1; }
;                     if (WB) { u32x4 w; w.x = cvt_pk_bf16(v0[0], v0[1]); w.y = cvt_pk_bf16(v0[2], v0[3]); w.z = cvt_pk_bf16(v1[0], v1[1]); w.w = cvt_pk_bf16(v1[2], v1[3]); *(u32x4*)(xb + off) = w; }
;                     ss += (v0[0] * v0[0] + v0[1] * v0[1]) + (v0[2] * v0[2] + v0[3] * v0[3]) + (v1[0] * v1[0] + v1[1] * v1[1]) + (v1[2] * v1[2] + v1[3] * v1[3]); }
;                 ss += __shfl_xor(ss, 16); ss += __shfl_xor(ss, 32);
;                 if (fq == 0) ssq[r * 16 + u.pn * 4 + wc] = ss; }
	v_add_f32_e32 v128, v128, v129
	ds_bpermute_b32 v129, v206, v128
	s_waitcnt lgkmcnt(0)
	v_add_f32_e32 v128, v128, v129
	s_and_saveexec_b64 s[50:51], vcc
	global_store_dword v[226:227], v128, off
	s_or_b64 exec, exec, s[50:51]
	v_lshl_add_u64 v[224:225], v[224:225], 0, s[82:83]
	v_lshl_add_u64 v[226:227], v[226:227], 0, s[86:87]
	s_waitcnt vmcnt(15)
	v_pk_fma_f32 v[12:13], v[12:13], s[40:41], v[144:145] op_sel_hi:[1,0,1]
	v_pk_fma_f32 v[14:15], v[14:15], s[40:41], v[146:147] op_sel_hi:[1,0,1]
	v_pk_fma_f32 v[4:5], v[4:5], s[40:41], v[148:149] op_sel_hi:[1,0,1]
	v_pk_fma_f32 v[6:7], v[6:7], s[40:41], v[150:151] op_sel_hi:[1,0,1]
	v_pk_fma_f32 v[8:9], v[8:9], s[40:41], v[152:153] op_sel_hi:[1,0,1]
	v_pk_fma_f32 v[10:11], v[10:11], s[40:41], v[154:155] op_sel_hi:[1,0,1]
	v_pk_fma_f32 v[0:1], v[0:1], s[40:41], v[156:157] op_sel_hi:[1,0,1]
	v_pk_fma_f32 v[2:3], v[2:3], s[40:41], v[158:159] op_sel_hi:[1,0,1]
	v_mul_f32_e32 v144, v13, v13
	v_mul_f32_e32 v145, v15, v15
	v_mul_f32_e32 v146, v5, v5
	v_mul_f32_e32 v147, v7, v7
	v_mul_f32_e32 v148, v9, v9
	v_mul_f32_e32 v149, v11, v11
	v_mul_f32_e32 v150, v1, v1
	v_mul_f32_e32 v151, v3, v3
	v_fmac_f32_e32 v144, v12, v12
	v_fmac_f32_e32 v145, v14, v14
	v_fmac_f32_e32 v146, v4, v4
	v_fmac_f32_e32 v147, v6, v6
	v_fmac_f32_e32 v148, v8, v8
	v_fmac_f32_e32 v149, v10, v10
	v_fmac_f32_e32 v150, v0, v0
	v_fmac_f32_e32 v151, v2, v2
	v_cvt_pk_bf16_f32 v152, v12, v13
	v_cvt_pk_bf16_f32 v153, v14, v15
	v_cvt_pk_bf16_f32 v154, v4, v5
	v_cvt_pk_bf16_f32 v155, v6, v7
	v_cvt_pk_bf16_f32 v156, v8, v9
	v_cvt_pk_bf16_f32 v157, v10, v11
	v_cvt_pk_bf16_f32 v158, v0, v1
	v_cvt_pk_bf16_f32 v159, v2, v3
	global_store_dwordx4 v[224:225], v[152:155], off
	global_store_dwordx4 v[224:225], v[156:159], off offset:256
	v_add_f32_e32 v144, v144, v145
	v_add_f32_e32 v146, v146, v147
	v_add_f32_e32 v148, v148, v149
	v_add_f32_e32 v150, v150, v151
	v_add_f32_e32 v144, v144, v146
	v_add_f32_e32 v148, v148, v150
	v_add_f32_e32 v144, v144, v148
	ds_bpermute_b32 v145, v205, v144
	s_waitcnt lgkmcnt(0)
	v_add_f32_e32 v144, v144, v145
	ds_bpermute_b32 v145, v206, v144
	s_waitcnt lgkmcnt(0)
	v_add_f32_e32 v144, v144, v145
	s_and_saveexec_b64 s[50:51], vcc
	global_store_dword v[226:227], v144, off
	s_or_b64 exec, exec, s[50:51]
	s_andn2_b64 vcc, exec, s[4:5]
	s_mov_b64 s[4:5], -1
	s_cbranch_vccnz .LBB0_338
	s_mov_b32 s9, s8
	s_mov_b32 s10, s8
	s_mov_b32 s11, s8
	s_waitcnt lgkmcnt(0)
	v_mov_b64_e32 v[0:1], s[8:9]
	v_mov_b64_e32 v[118:119], s[10:11]
	v_mov_b64_e32 v[114:115], s[10:11]
	v_mov_b64_e32 v[110:111], s[10:11]
	v_mov_b64_e32 v[102:103], s[10:11]
	v_mov_b64_e32 v[94:95], s[10:11]
	v_mov_b64_e32 v[86:87], s[10:11]
	v_mov_b64_e32 v[78:79], s[10:11]
	v_mov_b64_e32 v[70:71], s[10:11]
	v_mov_b64_e32 v[126:127], s[10:11]
	v_mov_b64_e32 v[122:123], s[10:11]
	v_mov_b64_e32 v[106:107], s[10:11]
	v_mov_b64_e32 v[98:99], s[10:11]
	v_mov_b64_e32 v[90:91], s[10:11]
	v_mov_b64_e32 v[82:83], s[10:11]
	v_mov_b64_e32 v[74:75], s[10:11]
	v_mov_b64_e32 v[66:67], s[10:11]
	v_mov_b64_e32 v[54:55], s[10:11]
	v_mov_b64_e32 v[50:51], s[10:11]
	v_mov_b64_e32 v[46:47], s[10:11]
	v_mov_b64_e32 v[38:39], s[10:11]
	v_mov_b64_e32 v[30:31], s[10:11]
	v_mov_b64_e32 v[22:23], s[10:11]
	v_mov_b64_e32 v[14:15], s[10:11]
	v_mov_b64_e32 v[4:5], s[8:9]
	v_mov_b64_e32 v[62:63], s[10:11]
	v_mov_b64_e32 v[58:59], s[10:11]
	v_mov_b64_e32 v[42:43], s[10:11]
	v_mov_b64_e32 v[34:35], s[10:11]
	v_mov_b64_e32 v[26:27], s[10:11]
	v_mov_b64_e32 v[18:19], s[10:11]
	v_mov_b64_e32 v[8:9], s[8:9]
	v_mov_b64_e32 v[2:3], s[10:11]
	v_mov_b64_e32 v[116:117], s[8:9]
	v_mov_b64_e32 v[112:113], s[8:9]
	v_mov_b64_e32 v[108:109], s[8:9]
	v_mov_b64_e32 v[100:101], s[8:9]
	v_mov_b64_e32 v[92:93], s[8:9]
	v_mov_b64_e32 v[84:85], s[8:9]
	v_mov_b64_e32 v[76:77], s[8:9]
	v_mov_b64_e32 v[68:69], s[8:9]
	v_mov_b64_e32 v[124:125], s[8:9]
	v_mov_b64_e32 v[120:121], s[8:9]
	v_mov_b64_e32 v[104:105], s[8:9]
	v_mov_b64_e32 v[96:97], s[8:9]
	v_mov_b64_e32 v[88:89], s[8:9]
	v_mov_b64_e32 v[80:81], s[8:9]
	v_mov_b64_e32 v[72:73], s[8:9]
	v_mov_b64_e32 v[64:65], s[8:9]
	v_mov_b64_e32 v[52:53], s[8:9]
	v_mov_b64_e32 v[48:49], s[8:9]
	v_mov_b64_e32 v[44:45], s[8:9]
	v_mov_b64_e32 v[36:37], s[8:9]
	v_mov_b64_e32 v[28:29], s[8:9]
	v_mov_b64_e32 v[20:21], s[8:9]
	v_mov_b64_e32 v[12:13], s[8:9]
	v_mov_b64_e32 v[6:7], s[10:11]
	v_mov_b64_e32 v[60:61], s[8:9]
	v_mov_b64_e32 v[56:57], s[8:9]
	v_mov_b64_e32 v[40:41], s[8:9]
	v_mov_b64_e32 v[32:33], s[8:9]
	v_mov_b64_e32 v[24:25], s[8:9]
	v_mov_b64_e32 v[16:17], s[8:9]
	v_mov_b64_e32 v[10:11], s[10:11]
	s_andn2_b64 vcc, exec, s[6:7]
	s_cbranch_vccnz .LBB0_337
	s_mov_b32 s100, 1
	s_branch .LBB0_337
